# as previous plus final-pass GA loads/stores widened to dwordx4 via v_permlane16_swap pairs
# speedup vs baseline: 1.0063x; 1.0025x over previous
; __device__ __forceinline__ unsigned cvt_pk_bf16(float lo, float hi) { unsigned r; asm volatile("v_cvt_pk_bf16_f32 %0, %1, %2" : "=v"(r) : "v"(lo), "v"(hi)); return r; }
; __device__ __forceinline__ float bflo(unsigned w) { return __uint_as_float(w << 16); }
; __device__ __forceinline__ float bfhi(unsigned w) { return __uint_as_float(w & 0xffff0000u); }
; template <bool DRY>
; __device__ __forceinline__ void attn_unit(const Args& a, LAS unsigned char* lds, int cidx, int h, int lane, int wave) {
;     ...
; #pragma unroll
;             for (int gq = 0; gq < 2; ++gq) {
;                 const int qi = qpos[gq] - Pu;
;                 const float dt = den[gq] + *(const float*)((const char*)Xd + (unsigned)qi * 4u) + *(const float*)((const char*)Xd + (unsigned)(512 + qi) * 4u);
;                 const float inv = 1.0f / dt;
;                 const unsigned x1o = ((unsigned)qi * 128 + 4 * fq) * 2u, x4o = ((unsigned)(512 + qi) * 128 + 4 * fq) * 2u;
;                 const unsigned go = ((unsigned)(seq_start + qpos[gq]) * AW + h * 128 + 4 * fq) * 2u;
; #pragma unroll
;                 for (int c = 0; c < 8; ++c) {
;                     bf16_t* gp = (bf16_t*)((char*)GA + go) - 16 * c + 16 * c;
;                     const u32x2 xa = *(const u32x2*)((const char*)X + x1o + 32 * c), xb = *(const u32x2*)((const char*)X + x4o + 32 * c);
;                     const f32x4 t = o[gq][c] + (f32x4){bflo(xa.x), bfhi(xa.x), bflo(xa.y), bfhi(xa.y)} + (f32x4){bflo(xb.x), bfhi(xb.x), bflo(xb.y), bfhi(xb.y)};
;                     const u32x2 gg = *(const u32x2*)(gp + 16 * c);
;                     u32x2 w; w.x = cvt_pk_bf16(t[0] * inv * bflo(gg.x), t[1] * inv * bfhi(gg.x)); w.y = cvt_pk_bf16(t[2] * inv * bflo(gg.y), t[3] * inv * bfhi(gg.y));
;                     if (!DRY || inv == 1.2345e33f) *(u32x2*)(gp + 16 * c) = w;
;                 }
.LBB0_606:
	v_lshlrev_b32_e32 v95, 5, v166
	v_and_b32_e32 v93, 8, v166
	v_mul_u32_u24_e32 v93, 3, v93
	v_subrev_u32_e32 v76, s50, v190
	v_add3_u32 v66, v192, v187, v93
	v_lshlrev_b32_e32 v72, 2, v76
	v_add_u32_e32 v73, 0x800, v72
	v_lshrrev_b32_e32 v94, 4, v76
	v_and_b32_e32 v68, 15, v76
	v_lshlrev_b32_e32 v68, 4, v68
	v_lshl_add_u32 v68, v94, 12, v68
	v_add_u32_e32 v68, v68, v95
	v_and_b32_e32 v94, 3, v76
	v_lshlrev_b32_e32 v94, 3, v94
	v_lshrrev_b32_e32 v69, 6, v76
	v_add_u32_e32 v94, v94, v69
	v_bfe_u32 v69, v76, 2, 4
	v_lshlrev_b32_e32 v69, 4, v69
	v_lshl_add_u32 v69, v94, 12, v69
	v_add_u32_e32 v69, v69, v95
	v_add_u32_e32 v69, 0x20000, v69
	v_subrev_u32_e32 v77, s50, v189
	v_add3_u32 v67, v191, v187, v93
	v_lshlrev_b32_e32 v74, 2, v77
	v_add_u32_e32 v75, 0x800, v74
	v_lshrrev_b32_e32 v94, 4, v77
	v_and_b32_e32 v70, 15, v77
	v_lshlrev_b32_e32 v70, 4, v70
	v_lshl_add_u32 v70, v94, 12, v70
	v_add_u32_e32 v70, v70, v95
	v_and_b32_e32 v94, 3, v77
	v_lshlrev_b32_e32 v94, 3, v94
	v_lshrrev_b32_e32 v71, 6, v77
	v_add_u32_e32 v94, v94, v71
	v_bfe_u32 v71, v77, 2, 4
	v_lshlrev_b32_e32 v71, 4, v71
	v_lshl_add_u32 v71, v94, 12, v71
	v_add_u32_e32 v71, v71, v95
	v_add_u32_e32 v71, 0x20000, v71
	global_load_dword v78, v72, s[30:31]
	global_load_dword v79, v73, s[30:31]
	global_load_dword v80, v74, s[30:31]
	global_load_dword v81, v75, s[30:31]
	global_load_dwordx4 v[196:199], v66, s[20:21]
	global_load_dwordx4 v[96:99], v68, s[22:23]
	global_load_dwordx4 v[100:103], v69, s[22:23]
	global_load_dwordx4 v[200:203], v66, s[20:21] offset:64
	global_load_dwordx4 v[104:107], v68, s[22:23] offset:1024
	global_load_dwordx4 v[108:111], v69, s[22:23] offset:1024
	global_load_dwordx4 v[204:207], v66, s[20:21] offset:128
	global_load_dwordx4 v[112:115], v68, s[22:23] offset:2048
	global_load_dwordx4 v[116:119], v69, s[22:23] offset:2048
	global_load_dwordx4 v[208:211], v66, s[20:21] offset:192
	global_load_dwordx4 v[120:123], v68, s[22:23] offset:3072
	global_load_dwordx4 v[124:127], v69, s[22:23] offset:3072
	global_load_dwordx4 v[212:215], v67, s[20:21]
	global_load_dwordx4 v[128:131], v70, s[22:23]
	global_load_dwordx4 v[132:135], v71, s[22:23]
	global_load_dwordx4 v[216:219], v67, s[20:21] offset:64
	global_load_dwordx4 v[136:139], v70, s[22:23] offset:1024
	global_load_dwordx4 v[140:143], v71, s[22:23] offset:1024
	global_load_dwordx4 v[220:223], v67, s[20:21] offset:128
	global_load_dwordx4 v[144:147], v70, s[22:23] offset:2048
	global_load_dwordx4 v[148:151], v71, s[22:23] offset:2048
	global_load_dwordx4 v[224:227], v67, s[20:21] offset:192
	global_load_dwordx4 v[152:155], v70, s[22:23] offset:3072
	global_load_dwordx4 v[156:159], v71, s[22:23] offset:3072
	s_waitcnt vmcnt(26)
	v_add_f32_e32 v92, v65, v78
	v_add_f32_e32 v92, v92, v79
	s_waitcnt vmcnt(24)
	v_add_f32_e32 v94, v64, v80
	v_add_f32_e32 v94, v94, v81
	v_div_scale_f32 v84, s[6:7], v92, v92, 1.0
	v_rcp_f32_e32 v85, v84
	v_div_scale_f32 v86, vcc, 1.0, v92, 1.0
	v_fma_f32 v87, -v84, v85, 1.0
	v_fmac_f32_e32 v85, v87, v85
	v_mul_f32_e32 v87, v86, v85
	v_fma_f32 v88, -v84, v87, v86
	v_fmac_f32_e32 v87, v88, v85
	v_fma_f32 v88, -v84, v87, v86
	v_div_fmas_f32 v87, v88, v85, v87
	v_div_fixup_f32 v82, v87, v92, 1.0
	v_div_scale_f32 v84, s[6:7], v94, v94, 1.0
	v_rcp_f32_e32 v85, v84
	v_div_scale_f32 v86, vcc, 1.0, v94, 1.0
	v_fma_f32 v87, -v84, v85, 1.0
	v_fmac_f32_e32 v85, v87, v85
	v_mul_f32_e32 v87, v86, v85
	v_fma_f32 v88, -v84, v87, v86
	v_fmac_f32_e32 v87, v88, v85
	v_fma_f32 v88, -v84, v87, v86
	v_div_fmas_f32 v87, v88, v85, v87
	v_div_fixup_f32 v83, v87, v94, 1.0
	s_waitcnt vmcnt(21)
	s_nop 1
	v_permlane16_swap_b32_e32 v196, v198
	v_permlane16_swap_b32_e32 v197, v199
	v_lshlrev_b32_e32 v84, 16, v96
	v_and_b32_e32 v85, 0xffff0000, v96
	v_lshlrev_b32_e32 v86, 16, v97
	v_and_b32_e32 v87, 0xffff0000, v97
	v_lshlrev_b32_e32 v92, 16, v100
	v_and_b32_e32 v93, 0xffff0000, v100
	v_lshlrev_b32_e32 v94, 16, v101
	v_and_b32_e32 v95, 0xffff0000, v101
	v_pk_add_f32 v[84:85], v[60:61], v[84:85]
	v_pk_add_f32 v[86:87], v[62:63], v[86:87]
	v_pk_add_f32 v[84:85], v[84:85], v[92:93]
	v_pk_add_f32 v[86:87], v[86:87], v[94:95]
	v_mul_f32_e32 v84, v82, v84
	v_mul_f32_e32 v85, v82, v85
	v_mul_f32_e32 v86, v82, v86
	v_mul_f32_e32 v87, v82, v87
	v_lshlrev_b32_e32 v92, 16, v196
	v_and_b32_e32 v93, 0xffff0000, v196
	v_lshlrev_b32_e32 v94, 16, v197
	v_and_b32_e32 v95, 0xffff0000, v197
	v_mul_f32_e32 v84, v84, v92
	v_mul_f32_e32 v85, v85, v93
	v_mul_f32_e32 v86, v86, v94
	v_mul_f32_e32 v87, v87, v95
	v_cvt_pk_bf16_f32 v88, v84, v85
	v_cvt_pk_bf16_f32 v89, v86, v87
	v_lshlrev_b32_e32 v84, 16, v98
	v_and_b32_e32 v85, 0xffff0000, v98
	v_lshlrev_b32_e32 v86, 16, v99
	v_and_b32_e32 v87, 0xffff0000, v99
	v_lshlrev_b32_e32 v92, 16, v102
	v_and_b32_e32 v93, 0xffff0000, v102
	v_lshlrev_b32_e32 v94, 16, v103
	v_and_b32_e32 v95, 0xffff0000, v103
	v_pk_add_f32 v[84:85], v[40:41], v[84:85]
	v_pk_add_f32 v[86:87], v[42:43], v[86:87]
	v_pk_add_f32 v[84:85], v[84:85], v[92:93]
	v_pk_add_f32 v[86:87], v[86:87], v[94:95]
	v_mul_f32_e32 v84, v82, v84
	v_mul_f32_e32 v85, v82, v85
	v_mul_f32_e32 v86, v82, v86
	v_mul_f32_e32 v87, v82, v87
	v_lshlrev_b32_e32 v92, 16, v198
	v_and_b32_e32 v93, 0xffff0000, v198
	v_lshlrev_b32_e32 v94, 16, v199
	v_and_b32_e32 v95, 0xffff0000, v199
	v_mul_f32_e32 v84, v84, v92
	v_mul_f32_e32 v85, v85, v93
	v_mul_f32_e32 v86, v86, v94
	v_mul_f32_e32 v87, v87, v95
	v_cvt_pk_bf16_f32 v90, v84, v85
	v_cvt_pk_bf16_f32 v91, v86, v87
	s_nop 1
	v_permlane16_swap_b32_e32 v88, v90
	v_permlane16_swap_b32_e32 v89, v91
	global_store_dwordx4 v66, v[88:91], s[20:21]
	s_waitcnt vmcnt(19)
; __device__ __forceinline__ unsigned cvt_pk_bf16(float lo, float hi) { unsigned r; asm volatile("v_cvt_pk_bf16_f32 %0, %1, %2" : "=v"(r) : "v"(lo), "v"(hi)); return r; }
; __device__ __forceinline__ float bflo(unsigned w) { return __uint_as_float(w << 16); }
; __device__ __forceinline__ float bfhi(unsigned w) { return __uint_as_float(w & 0xffff0000u); }
; template <bool DRY>
; __device__ __forceinline__ void attn_unit(const Args& a, LAS unsigned char* lds, int cidx, int h, int lane, int wave) {
;     ...
; #pragma unroll
;                 for (int c = 0; c < 8; ++c) {
;                     bf16_t* gp = (bf16_t*)((char*)GA + go) - 16 * c + 16 * c;
;                     const u32x2 xa = *(const u32x2*)((const char*)X + x1o + 32 * c), xb = *(const u32x2*)((const char*)X + x4o + 32 * c);
;                     const f32x4 t = o[gq][c] + (f32x4){bflo(xa.x), bfhi(xa.x), bflo(xa.y), bfhi(xa.y)} + (f32x4){bflo(xb.x), bfhi(xb.x), bflo(xb.y), bfhi(xb.y)};
;                     const u32x2 gg = *(const u32x2*)(gp + 16 * c);
;                     u32x2 w; w.x = cvt_pk_bf16(t[0] * inv * bflo(gg.x), t[1] * inv * bfhi(gg.x)); w.y = cvt_pk_bf16(t[2] * inv * bflo(gg.y), t[3] * inv * bfhi(gg.y));
;                     if (!DRY || inv == 1.2345e33f) *(u32x2*)(gp + 16 * c) = w;
;                 }
	s_nop 1
	v_permlane16_swap_b32_e32 v200, v202
	v_permlane16_swap_b32_e32 v201, v203
	v_lshlrev_b32_e32 v84, 16, v104
	v_and_b32_e32 v85, 0xffff0000, v104
	v_lshlrev_b32_e32 v86, 16, v105
	v_and_b32_e32 v87, 0xffff0000, v105
	v_lshlrev_b32_e32 v92, 16, v108
	v_and_b32_e32 v93, 0xffff0000, v108
	v_lshlrev_b32_e32 v94, 16, v109
	v_and_b32_e32 v95, 0xffff0000, v109
	v_pk_add_f32 v[84:85], v[56:57], v[84:85]
	v_pk_add_f32 v[86:87], v[58:59], v[86:87]
	v_pk_add_f32 v[84:85], v[84:85], v[92:93]
	v_pk_add_f32 v[86:87], v[86:87], v[94:95]
	v_mul_f32_e32 v84, v82, v84
	v_mul_f32_e32 v85, v82, v85
	v_mul_f32_e32 v86, v82, v86
	v_mul_f32_e32 v87, v82, v87
	v_lshlrev_b32_e32 v92, 16, v200
	v_and_b32_e32 v93, 0xffff0000, v200
	v_lshlrev_b32_e32 v94, 16, v201
	v_and_b32_e32 v95, 0xffff0000, v201
	v_mul_f32_e32 v84, v84, v92
	v_mul_f32_e32 v85, v85, v93
	v_mul_f32_e32 v86, v86, v94
	v_mul_f32_e32 v87, v87, v95
	v_cvt_pk_bf16_f32 v88, v84, v85
	v_cvt_pk_bf16_f32 v89, v86, v87
	v_lshlrev_b32_e32 v84, 16, v106
	v_and_b32_e32 v85, 0xffff0000, v106
	v_lshlrev_b32_e32 v86, 16, v107
	v_and_b32_e32 v87, 0xffff0000, v107
	v_lshlrev_b32_e32 v92, 16, v110
	v_and_b32_e32 v93, 0xffff0000, v110
	v_lshlrev_b32_e32 v94, 16, v111
	v_and_b32_e32 v95, 0xffff0000, v111
	v_pk_add_f32 v[84:85], v[52:53], v[84:85]
	v_pk_add_f32 v[86:87], v[54:55], v[86:87]
	v_pk_add_f32 v[84:85], v[84:85], v[92:93]
	v_pk_add_f32 v[86:87], v[86:87], v[94:95]
	v_mul_f32_e32 v84, v82, v84
	v_mul_f32_e32 v85, v82, v85
	v_mul_f32_e32 v86, v82, v86
	v_mul_f32_e32 v87, v82, v87
	v_lshlrev_b32_e32 v92, 16, v202
	v_and_b32_e32 v93, 0xffff0000, v202
	v_lshlrev_b32_e32 v94, 16, v203
	v_and_b32_e32 v95, 0xffff0000, v203
	v_mul_f32_e32 v84, v84, v92
	v_mul_f32_e32 v85, v85, v93
	v_mul_f32_e32 v86, v86, v94
	v_mul_f32_e32 v87, v87, v95
	v_cvt_pk_bf16_f32 v90, v84, v85
	v_cvt_pk_bf16_f32 v91, v86, v87
	s_nop 1
	v_permlane16_swap_b32_e32 v88, v90
	v_permlane16_swap_b32_e32 v89, v91
	global_store_dwordx4 v66, v[88:91], s[20:21] offset:64
	s_waitcnt vmcnt(17)
	s_nop 1
	v_permlane16_swap_b32_e32 v204, v206
	v_permlane16_swap_b32_e32 v205, v207
	v_lshlrev_b32_e32 v84, 16, v112
	v_and_b32_e32 v85, 0xffff0000, v112
	v_lshlrev_b32_e32 v86, 16, v113
	v_and_b32_e32 v87, 0xffff0000, v113
	v_lshlrev_b32_e32 v92, 16, v116
	v_and_b32_e32 v93, 0xffff0000, v116
	v_lshlrev_b32_e32 v94, 16, v117
	v_and_b32_e32 v95, 0xffff0000, v117
	v_pk_add_f32 v[84:85], v[48:49], v[84:85]
	v_pk_add_f32 v[86:87], v[50:51], v[86:87]
	v_pk_add_f32 v[84:85], v[84:85], v[92:93]
	v_pk_add_f32 v[86:87], v[86:87], v[94:95]
	v_mul_f32_e32 v84, v82, v84
	v_mul_f32_e32 v85, v82, v85
	v_mul_f32_e32 v86, v82, v86
	v_mul_f32_e32 v87, v82, v87
	v_lshlrev_b32_e32 v92, 16, v204
	v_and_b32_e32 v93, 0xffff0000, v204
	v_lshlrev_b32_e32 v94, 16, v205
	v_and_b32_e32 v95, 0xffff0000, v205
	v_mul_f32_e32 v84, v84, v92
	v_mul_f32_e32 v85, v85, v93
	v_mul_f32_e32 v86, v86, v94
	v_mul_f32_e32 v87, v87, v95
	v_cvt_pk_bf16_f32 v88, v84, v85
	v_cvt_pk_bf16_f32 v89, v86, v87
	v_lshlrev_b32_e32 v84, 16, v114
	v_and_b32_e32 v85, 0xffff0000, v114
	v_lshlrev_b32_e32 v86, 16, v115
	v_and_b32_e32 v87, 0xffff0000, v115
	v_lshlrev_b32_e32 v92, 16, v118
	v_and_b32_e32 v93, 0xffff0000, v118
	v_lshlrev_b32_e32 v94, 16, v119
	v_and_b32_e32 v95, 0xffff0000, v119
	v_pk_add_f32 v[84:85], v[44:45], v[84:85]
	v_pk_add_f32 v[86:87], v[46:47], v[86:87]
	v_pk_add_f32 v[84:85], v[84:85], v[92:93]
	v_pk_add_f32 v[86:87], v[86:87], v[94:95]
	v_mul_f32_e32 v84, v82, v84
	v_mul_f32_e32 v85, v82, v85
	v_mul_f32_e32 v86, v82, v86
	v_mul_f32_e32 v87, v82, v87
	v_lshlrev_b32_e32 v92, 16, v206
	v_and_b32_e32 v93, 0xffff0000, v206
	v_lshlrev_b32_e32 v94, 16, v207
	v_and_b32_e32 v95, 0xffff0000, v207
	v_mul_f32_e32 v84, v84, v92
	v_mul_f32_e32 v85, v85, v93
	v_mul_f32_e32 v86, v86, v94
	v_mul_f32_e32 v87, v87, v95
	v_cvt_pk_bf16_f32 v90, v84, v85
	v_cvt_pk_bf16_f32 v91, v86, v87
	s_nop 1
	v_permlane16_swap_b32_e32 v88, v90
	v_permlane16_swap_b32_e32 v89, v91
	global_store_dwordx4 v66, v[88:91], s[20:21] offset:128
	s_waitcnt vmcnt(15)
	s_nop 1
	v_permlane16_swap_b32_e32 v208, v210
	v_permlane16_swap_b32_e32 v209, v211
	v_lshlrev_b32_e32 v84, 16, v120
	v_and_b32_e32 v85, 0xffff0000, v120
	v_lshlrev_b32_e32 v86, 16, v121
	v_and_b32_e32 v87, 0xffff0000, v121
	v_lshlrev_b32_e32 v92, 16, v124
	v_and_b32_e32 v93, 0xffff0000, v124
	v_lshlrev_b32_e32 v94, 16, v125
	v_and_b32_e32 v95, 0xffff0000, v125
	v_pk_add_f32 v[84:85], v[36:37], v[84:85]
	v_pk_add_f32 v[86:87], v[38:39], v[86:87]
	v_pk_add_f32 v[84:85], v[84:85], v[92:93]
	v_pk_add_f32 v[86:87], v[86:87], v[94:95]
	v_mul_f32_e32 v84, v82, v84
	v_mul_f32_e32 v85, v82, v85
	v_mul_f32_e32 v86, v82, v86
	v_mul_f32_e32 v87, v82, v87
	v_lshlrev_b32_e32 v92, 16, v208
	v_and_b32_e32 v93, 0xffff0000, v208
	v_lshlrev_b32_e32 v94, 16, v209
	v_and_b32_e32 v95, 0xffff0000, v209
	v_mul_f32_e32 v84, v84, v92
	v_mul_f32_e32 v85, v85, v93
	v_mul_f32_e32 v86, v86, v94
	v_mul_f32_e32 v87, v87, v95
	v_cvt_pk_bf16_f32 v88, v84, v85
	v_cvt_pk_bf16_f32 v89, v86, v87
	v_lshlrev_b32_e32 v84, 16, v122
	v_and_b32_e32 v85, 0xffff0000, v122
	v_lshlrev_b32_e32 v86, 16, v123
	v_and_b32_e32 v87, 0xffff0000, v123
	v_lshlrev_b32_e32 v92, 16, v126
	v_and_b32_e32 v93, 0xffff0000, v126
	v_lshlrev_b32_e32 v94, 16, v127
	v_and_b32_e32 v95, 0xffff0000, v127
	v_pk_add_f32 v[84:85], v[32:33], v[84:85]
	v_pk_add_f32 v[86:87], v[34:35], v[86:87]
	v_pk_add_f32 v[84:85], v[84:85], v[92:93]
	v_pk_add_f32 v[86:87], v[86:87], v[94:95]
	v_mul_f32_e32 v84, v82, v84
	v_mul_f32_e32 v85, v82, v85
	v_mul_f32_e32 v86, v82, v86
	v_mul_f32_e32 v87, v82, v87
	v_lshlrev_b32_e32 v92, 16, v210
	v_and_b32_e32 v93, 0xffff0000, v210
	v_lshlrev_b32_e32 v94, 16, v211
	v_and_b32_e32 v95, 0xffff0000, v211
	v_mul_f32_e32 v84, v84, v92
	v_mul_f32_e32 v85, v85, v93
	v_mul_f32_e32 v86, v86, v94
	v_mul_f32_e32 v87, v87, v95
	v_cvt_pk_bf16_f32 v90, v84, v85
	v_cvt_pk_bf16_f32 v91, v86, v87
	s_nop 1
	v_permlane16_swap_b32_e32 v88, v90
	v_permlane16_swap_b32_e32 v89, v91
	global_store_dwordx4 v66, v[88:91], s[20:21] offset:192
	s_waitcnt vmcnt(13)
; __device__ __forceinline__ unsigned cvt_pk_bf16(float lo, float hi) { unsigned r; asm volatile("v_cvt_pk_bf16_f32 %0, %1, %2" : "=v"(r) : "v"(lo), "v"(hi)); return r; }
; __device__ __forceinline__ float bflo(unsigned w) { return __uint_as_float(w << 16); }
; __device__ __forceinline__ float bfhi(unsigned w) { return __uint_as_float(w & 0xffff0000u); }
; template <bool DRY>
; __device__ __forceinline__ void attn_unit(const Args& a, LAS unsigned char* lds, int cidx, int h, int lane, int wave) {
;     ...
; #pragma unroll
;                 for (int c = 0; c < 8; ++c) {
;                     bf16_t* gp = (bf16_t*)((char*)GA + go) - 16 * c + 16 * c;
;                     const u32x2 xa = *(const u32x2*)((const char*)X + x1o + 32 * c), xb = *(const u32x2*)((const char*)X + x4o + 32 * c);
;                     const f32x4 t = o[gq][c] + (f32x4){bflo(xa.x), bfhi(xa.x), bflo(xa.y), bfhi(xa.y)} + (f32x4){bflo(xb.x), bfhi(xb.x), bflo(xb.y), bfhi(xb.y)};
;                     const u32x2 gg = *(const u32x2*)(gp + 16 * c);
;                     u32x2 w; w.x = cvt_pk_bf16(t[0] * inv * bflo(gg.x), t[1] * inv * bfhi(gg.x)); w.y = cvt_pk_bf16(t[2] * inv * bflo(gg.y), t[3] * inv * bfhi(gg.y));
;                     if (!DRY || inv == 1.2345e33f) *(u32x2*)(gp + 16 * c) = w;
;                 }
	s_nop 1
	v_permlane16_swap_b32_e32 v212, v214
	v_permlane16_swap_b32_e32 v213, v215
	v_lshlrev_b32_e32 v84, 16, v128
	v_and_b32_e32 v85, 0xffff0000, v128
	v_lshlrev_b32_e32 v86, 16, v129
	v_and_b32_e32 v87, 0xffff0000, v129
	v_lshlrev_b32_e32 v92, 16, v132
	v_and_b32_e32 v93, 0xffff0000, v132
	v_lshlrev_b32_e32 v94, 16, v133
	v_and_b32_e32 v95, 0xffff0000, v133
	v_pk_add_f32 v[84:85], v[28:29], v[84:85]
	v_pk_add_f32 v[86:87], v[30:31], v[86:87]
	v_pk_add_f32 v[84:85], v[84:85], v[92:93]
	v_pk_add_f32 v[86:87], v[86:87], v[94:95]
	v_mul_f32_e32 v84, v83, v84
	v_mul_f32_e32 v85, v83, v85
	v_mul_f32_e32 v86, v83, v86
	v_mul_f32_e32 v87, v83, v87
	v_lshlrev_b32_e32 v92, 16, v212
	v_and_b32_e32 v93, 0xffff0000, v212
	v_lshlrev_b32_e32 v94, 16, v213
	v_and_b32_e32 v95, 0xffff0000, v213
	v_mul_f32_e32 v84, v84, v92
	v_mul_f32_e32 v85, v85, v93
	v_mul_f32_e32 v86, v86, v94
	v_mul_f32_e32 v87, v87, v95
	v_cvt_pk_bf16_f32 v88, v84, v85
	v_cvt_pk_bf16_f32 v89, v86, v87
	v_lshlrev_b32_e32 v84, 16, v130
	v_and_b32_e32 v85, 0xffff0000, v130
	v_lshlrev_b32_e32 v86, 16, v131
	v_and_b32_e32 v87, 0xffff0000, v131
	v_lshlrev_b32_e32 v92, 16, v134
	v_and_b32_e32 v93, 0xffff0000, v134
	v_lshlrev_b32_e32 v94, 16, v135
	v_and_b32_e32 v95, 0xffff0000, v135
	v_pk_add_f32 v[84:85], v[24:25], v[84:85]
	v_pk_add_f32 v[86:87], v[26:27], v[86:87]
	v_pk_add_f32 v[84:85], v[84:85], v[92:93]
	v_pk_add_f32 v[86:87], v[86:87], v[94:95]
	v_mul_f32_e32 v84, v83, v84
	v_mul_f32_e32 v85, v83, v85
	v_mul_f32_e32 v86, v83, v86
	v_mul_f32_e32 v87, v83, v87
	v_lshlrev_b32_e32 v92, 16, v214
	v_and_b32_e32 v93, 0xffff0000, v214
	v_lshlrev_b32_e32 v94, 16, v215
	v_and_b32_e32 v95, 0xffff0000, v215
	v_mul_f32_e32 v84, v84, v92
	v_mul_f32_e32 v85, v85, v93
	v_mul_f32_e32 v86, v86, v94
	v_mul_f32_e32 v87, v87, v95
	v_cvt_pk_bf16_f32 v90, v84, v85
	v_cvt_pk_bf16_f32 v91, v86, v87
	s_nop 1
	v_permlane16_swap_b32_e32 v88, v90
	v_permlane16_swap_b32_e32 v89, v91
	global_store_dwordx4 v67, v[88:91], s[20:21]
	s_waitcnt vmcnt(11)
	s_nop 1
	v_permlane16_swap_b32_e32 v216, v218
	v_permlane16_swap_b32_e32 v217, v219
	v_lshlrev_b32_e32 v84, 16, v136
	v_and_b32_e32 v85, 0xffff0000, v136
	v_lshlrev_b32_e32 v86, 16, v137
	v_and_b32_e32 v87, 0xffff0000, v137
	v_lshlrev_b32_e32 v92, 16, v140
	v_and_b32_e32 v93, 0xffff0000, v140
	v_lshlrev_b32_e32 v94, 16, v141
	v_and_b32_e32 v95, 0xffff0000, v141
	v_pk_add_f32 v[84:85], v[20:21], v[84:85]
	v_pk_add_f32 v[86:87], v[22:23], v[86:87]
	v_pk_add_f32 v[84:85], v[84:85], v[92:93]
	v_pk_add_f32 v[86:87], v[86:87], v[94:95]
	v_mul_f32_e32 v84, v83, v84
	v_mul_f32_e32 v85, v83, v85
	v_mul_f32_e32 v86, v83, v86
	v_mul_f32_e32 v87, v83, v87
	v_lshlrev_b32_e32 v92, 16, v216
	v_and_b32_e32 v93, 0xffff0000, v216
	v_lshlrev_b32_e32 v94, 16, v217
	v_and_b32_e32 v95, 0xffff0000, v217
	v_mul_f32_e32 v84, v84, v92
	v_mul_f32_e32 v85, v85, v93
	v_mul_f32_e32 v86, v86, v94
	v_mul_f32_e32 v87, v87, v95
	v_cvt_pk_bf16_f32 v88, v84, v85
	v_cvt_pk_bf16_f32 v89, v86, v87
	v_lshlrev_b32_e32 v84, 16, v138
	v_and_b32_e32 v85, 0xffff0000, v138
	v_lshlrev_b32_e32 v86, 16, v139
	v_and_b32_e32 v87, 0xffff0000, v139
	v_lshlrev_b32_e32 v92, 16, v142
	v_and_b32_e32 v93, 0xffff0000, v142
	v_lshlrev_b32_e32 v94, 16, v143
	v_and_b32_e32 v95, 0xffff0000, v143
	v_pk_add_f32 v[84:85], v[16:17], v[84:85]
	v_pk_add_f32 v[86:87], v[18:19], v[86:87]
	v_pk_add_f32 v[84:85], v[84:85], v[92:93]
	v_pk_add_f32 v[86:87], v[86:87], v[94:95]
	v_mul_f32_e32 v84, v83, v84
	v_mul_f32_e32 v85, v83, v85
	v_mul_f32_e32 v86, v83, v86
	v_mul_f32_e32 v87, v83, v87
	v_lshlrev_b32_e32 v92, 16, v218
	v_and_b32_e32 v93, 0xffff0000, v218
	v_lshlrev_b32_e32 v94, 16, v219
	v_and_b32_e32 v95, 0xffff0000, v219
	v_mul_f32_e32 v84, v84, v92
	v_mul_f32_e32 v85, v85, v93
	v_mul_f32_e32 v86, v86, v94
	v_mul_f32_e32 v87, v87, v95
	v_cvt_pk_bf16_f32 v90, v84, v85
	v_cvt_pk_bf16_f32 v91, v86, v87
	s_nop 1
	v_permlane16_swap_b32_e32 v88, v90
	v_permlane16_swap_b32_e32 v89, v91
	global_store_dwordx4 v67, v[88:91], s[20:21] offset:64
	s_waitcnt vmcnt(9)
; __device__ __forceinline__ unsigned cvt_pk_bf16(float lo, float hi) { unsigned r; asm volatile("v_cvt_pk_bf16_f32 %0, %1, %2" : "=v"(r) : "v"(lo), "v"(hi)); return r; }
; __device__ __forceinline__ float bflo(unsigned w) { return __uint_as_float(w << 16); }
; __device__ __forceinline__ float bfhi(unsigned w) { return __uint_as_float(w & 0xffff0000u); }
; template <bool DRY>
; __device__ __forceinline__ void attn_unit(const Args& a, LAS unsigned char* lds, int cidx, int h, int lane, int wave) {
;     ...
; #pragma unroll
;                 for (int c = 0; c < 8; ++c) {
;                     bf16_t* gp = (bf16_t*)((char*)GA + go) - 16 * c + 16 * c;
;                     const u32x2 xa = *(const u32x2*)((const char*)X + x1o + 32 * c), xb = *(const u32x2*)((const char*)X + x4o + 32 * c);
;                     const f32x4 t = o[gq][c] + (f32x4){bflo(xa.x), bfhi(xa.x), bflo(xa.y), bfhi(xa.y)} + (f32x4){bflo(xb.x), bfhi(xb.x), bflo(xb.y), bfhi(xb.y)};
;                     const u32x2 gg = *(const u32x2*)(gp + 16 * c);
;                     u32x2 w; w.x = cvt_pk_bf16(t[0] * inv * bflo(gg.x), t[1] * inv * bfhi(gg.x)); w.y = cvt_pk_bf16(t[2] * inv * bflo(gg.y), t[3] * inv * bfhi(gg.y));
;                     if (!DRY || inv == 1.2345e33f) *(u32x2*)(gp + 16 * c) = w;
;                 }
	s_nop 1
	v_permlane16_swap_b32_e32 v220, v222
	v_permlane16_swap_b32_e32 v221, v223
	v_lshlrev_b32_e32 v84, 16, v144
	v_and_b32_e32 v85, 0xffff0000, v144
	v_lshlrev_b32_e32 v86, 16, v145
	v_and_b32_e32 v87, 0xffff0000, v145
	v_lshlrev_b32_e32 v92, 16, v148
	v_and_b32_e32 v93, 0xffff0000, v148
	v_lshlrev_b32_e32 v94, 16, v149
	v_and_b32_e32 v95, 0xffff0000, v149
	v_pk_add_f32 v[84:85], v[12:13], v[84:85]
	v_pk_add_f32 v[86:87], v[14:15], v[86:87]
	v_pk_add_f32 v[84:85], v[84:85], v[92:93]
	v_pk_add_f32 v[86:87], v[86:87], v[94:95]
	v_mul_f32_e32 v84, v83, v84
	v_mul_f32_e32 v85, v83, v85
	v_mul_f32_e32 v86, v83, v86
	v_mul_f32_e32 v87, v83, v87
	v_lshlrev_b32_e32 v92, 16, v220
	v_and_b32_e32 v93, 0xffff0000, v220
	v_lshlrev_b32_e32 v94, 16, v221
	v_and_b32_e32 v95, 0xffff0000, v221
	v_mul_f32_e32 v84, v84, v92
	v_mul_f32_e32 v85, v85, v93
	v_mul_f32_e32 v86, v86, v94
	v_mul_f32_e32 v87, v87, v95
	v_cvt_pk_bf16_f32 v88, v84, v85
	v_cvt_pk_bf16_f32 v89, v86, v87
	v_lshlrev_b32_e32 v84, 16, v146
	v_and_b32_e32 v85, 0xffff0000, v146
	v_lshlrev_b32_e32 v86, 16, v147
	v_and_b32_e32 v87, 0xffff0000, v147
	v_lshlrev_b32_e32 v92, 16, v150
	v_and_b32_e32 v93, 0xffff0000, v150
	v_lshlrev_b32_e32 v94, 16, v151
	v_and_b32_e32 v95, 0xffff0000, v151
	v_pk_add_f32 v[84:85], v[8:9], v[84:85]
	v_pk_add_f32 v[86:87], v[10:11], v[86:87]
	v_pk_add_f32 v[84:85], v[84:85], v[92:93]
	v_pk_add_f32 v[86:87], v[86:87], v[94:95]
	v_mul_f32_e32 v84, v83, v84
	v_mul_f32_e32 v85, v83, v85
	v_mul_f32_e32 v86, v83, v86
	v_mul_f32_e32 v87, v83, v87
	v_lshlrev_b32_e32 v92, 16, v222
	v_and_b32_e32 v93, 0xffff0000, v222
	v_lshlrev_b32_e32 v94, 16, v223
	v_and_b32_e32 v95, 0xffff0000, v223
	v_mul_f32_e32 v84, v84, v92
	v_mul_f32_e32 v85, v85, v93
	v_mul_f32_e32 v86, v86, v94
	v_mul_f32_e32 v87, v87, v95
	v_cvt_pk_bf16_f32 v90, v84, v85
	v_cvt_pk_bf16_f32 v91, v86, v87
	s_nop 1
	v_permlane16_swap_b32_e32 v88, v90
	v_permlane16_swap_b32_e32 v89, v91
	global_store_dwordx4 v67, v[88:91], s[20:21] offset:128
	s_waitcnt vmcnt(7)
	s_nop 1
	v_permlane16_swap_b32_e32 v224, v226
	v_permlane16_swap_b32_e32 v225, v227
	v_lshlrev_b32_e32 v84, 16, v152
	v_and_b32_e32 v85, 0xffff0000, v152
	v_lshlrev_b32_e32 v86, 16, v153
	v_and_b32_e32 v87, 0xffff0000, v153
	v_lshlrev_b32_e32 v92, 16, v156
	v_and_b32_e32 v93, 0xffff0000, v156
	v_lshlrev_b32_e32 v94, 16, v157
	v_and_b32_e32 v95, 0xffff0000, v157
	v_pk_add_f32 v[84:85], v[4:5], v[84:85]
	v_pk_add_f32 v[86:87], v[6:7], v[86:87]
	v_pk_add_f32 v[84:85], v[84:85], v[92:93]
	v_pk_add_f32 v[86:87], v[86:87], v[94:95]
	v_mul_f32_e32 v84, v83, v84
	v_mul_f32_e32 v85, v83, v85
	v_mul_f32_e32 v86, v83, v86
	v_mul_f32_e32 v87, v83, v87
	v_lshlrev_b32_e32 v92, 16, v224
	v_and_b32_e32 v93, 0xffff0000, v224
	v_lshlrev_b32_e32 v94, 16, v225
	v_and_b32_e32 v95, 0xffff0000, v225
	v_mul_f32_e32 v84, v84, v92
	v_mul_f32_e32 v85, v85, v93
	v_mul_f32_e32 v86, v86, v94
	v_mul_f32_e32 v87, v87, v95
	v_cvt_pk_bf16_f32 v88, v84, v85
	v_cvt_pk_bf16_f32 v89, v86, v87
	v_lshlrev_b32_e32 v84, 16, v154
	v_and_b32_e32 v85, 0xffff0000, v154
	v_lshlrev_b32_e32 v86, 16, v155
	v_and_b32_e32 v87, 0xffff0000, v155
	v_lshlrev_b32_e32 v92, 16, v158
	v_and_b32_e32 v93, 0xffff0000, v158
	v_lshlrev_b32_e32 v94, 16, v159
	v_and_b32_e32 v95, 0xffff0000, v159
	v_pk_add_f32 v[84:85], v[0:1], v[84:85]
	v_pk_add_f32 v[86:87], v[2:3], v[86:87]
	v_pk_add_f32 v[84:85], v[84:85], v[92:93]
	v_pk_add_f32 v[86:87], v[86:87], v[94:95]
	v_mul_f32_e32 v84, v83, v84
	v_mul_f32_e32 v85, v83, v85
	v_mul_f32_e32 v86, v83, v86
	v_mul_f32_e32 v87, v83, v87
	v_lshlrev_b32_e32 v92, 16, v226
	v_and_b32_e32 v93, 0xffff0000, v226
	v_lshlrev_b32_e32 v94, 16, v227
	v_and_b32_e32 v95, 0xffff0000, v227
	v_mul_f32_e32 v84, v84, v92
	v_mul_f32_e32 v85, v85, v93
	v_mul_f32_e32 v86, v86, v94
	v_mul_f32_e32 v87, v87, v95
	v_cvt_pk_bf16_f32 v90, v84, v85
	v_cvt_pk_bf16_f32 v91, v86, v87
	s_nop 1
	v_permlane16_swap_b32_e32 v88, v90
	v_permlane16_swap_b32_e32 v89, v91
	global_store_dwordx4 v67, v[88:91], s[20:21] offset:192
	s_branch .LBB0_595
